# GEMM phase prologue (gate_up, residual GEMMs): second LDS-DMA batch issued together with the first
# baseline (speedup 1.0000x reference)
.LBB0_809:
	s_andn2_b64 vcc, exec, s[4:5]
	s_cbranch_vccnz .LBB0_849
	v_bfe_i32 v2, v170, 27, 1
	v_lshlrev_b32_e32 v0, 4, v170
	v_lshrrev_b32_e32 v2, 22, v2
	v_add_u32_e32 v2, v0, v2
	v_and_b32_e32 v2, 0xfffffc00, v2
	v_sub_u32_e32 v2, v0, v2
	s_waitcnt lgkmcnt(0)
	v_ashrrev_i32_e32 v1, 31, v170
	v_lshrrev_b32_e32 v3, 4, v2
	v_lshrrev_b32_e32 v1, 26, v1
	v_bitop3_b32 v2, v3, v2, 32 bitop3:0x6c
	v_add_u32_e32 v1, v170, v1
	v_ashrrev_i32_e32 v4, 31, v2
	v_ashrrev_i32_e32 v1, 6, v1
	v_lshrrev_b32_e32 v4, 26, v4
	v_lshlrev_b32_e32 v3, 3, v1
	v_add_u32_e32 v4, v2, v4
	v_and_b32_e32 v3, -16, v3
	v_ashrrev_i32_e32 v5, 6, v4
	v_lshlrev_b32_e32 v1, 5, v1
	v_add_u32_e32 v3, v5, v3
	v_and_b32_e32 v14, 32, v1
	v_and_b32_e32 v1, 0xc0, v4
	v_sub_u32_e32 v1, v2, v1
	v_lshlrev_b32_e32 v2, 1, v3
	v_lshrrev_b32_e32 v4, 2, v3
	v_and_b32_e32 v5, 3, v5
	s_mov_b32 s2, 0x7fffffe0
	v_ashrrev_i16_sdwa v1, v185, sext(v1) dst_sel:DWORD dst_unused:UNUSED_PAD src0_sel:DWORD src1_sel:BYTE_0
	v_and_b32_e32 v2, 24, v2
	v_and_b32_e32 v4, 4, v4
	v_and_or_b32 v5, v3, s2, v5
	v_bfe_i32 v15, v1, 0, 16
	v_or3_b32 v2, v5, v4, v2
	v_add_u32_e32 v1, v14, v15
	v_mul_lo_u32 v16, s41, v3
	v_mul_lo_u32 v2, s41, v2
	v_add_u32_e32 v0, 0x2000, v0
	v_add_lshl_u32 v138, v16, v1, 1
	v_add_lshl_u32 v8, v2, v1, 1
	v_ashrrev_i32_e32 v1, 31, v0
	v_lshrrev_b32_e32 v1, 22, v1
	v_add_u32_e32 v1, v0, v1
	v_ashrrev_i32_e32 v1, 10, v1
	v_mul_i32_i24_e32 v2, 0x400, v1
	v_sub_u32_e32 v0, v0, v2
	v_lshrrev_b32_e32 v2, 4, v0
	v_bitop3_b32 v0, v2, v0, 32 bitop3:0x6c
	v_ashrrev_i32_e32 v3, 31, v0
	v_lshrrev_b32_e32 v3, 26, v3
	v_lshlrev_b32_e32 v2, 3, v1
	v_add_u32_e32 v3, v0, v3
	v_and_b32_e32 v2, -16, v2
	v_ashrrev_i32_e32 v4, 6, v3
	v_lshlrev_b32_e32 v1, 5, v1
	s_ashr_i32 s43, s40, 6
	s_lshl_b32 s6, s41, 9
	s_ashr_i32 s42, s40, 8
	v_add_u32_e32 v2, v4, v2
	v_and_b32_e32 v17, 32, v1
	v_and_b32_e32 v1, 0xc0, v3
	s_lshl_b32 s68, s41, 8
	s_lshl_b32 s7, s43, 10
	s_mul_i32 s4, s6, s17
	v_sub_u32_e32 v0, v0, v1
	v_lshlrev_b32_e32 v1, 1, v2
	v_lshrrev_b32_e32 v3, 2, v2
	v_and_b32_e32 v4, 3, v4
	s_mul_hi_i32 s5, s6, s17
	s_add_u32 s4, s50, s4
	v_ashrrev_i16_sdwa v0, v185, sext(v0) dst_sel:DWORD dst_unused:UNUSED_PAD src0_sel:DWORD src1_sel:BYTE_0
	v_and_b32_e32 v1, 24, v1
	v_and_b32_e32 v3, 4, v3
	v_and_or_b32 v4, v2, s2, v4
	s_addc_u32 s5, s51, s5
	s_add_i32 s8, s7, 0
	v_bfe_i32 v18, v0, 0, 16
	v_or3_b32 v1, v4, v3, v1
	s_add_i32 m0, s8, 0x10000
	v_add_u32_e32 v0, v17, v18
	v_mul_lo_u32 v1, s41, v1
	global_load_lds_dwordx4 v8, s[4:5]
	s_add_i32 m0, s8, 0x12000
	v_add_lshl_u32 v142, v1, v0, 1
	s_add_u32 s30, s4, s68
	global_load_lds_dwordx4 v142, s[4:5]
	s_addc_u32 s31, s5, 0
	s_add_i32 m0, s8, 0x14000
	v_writelane_b32 v252, s36, 2
	s_mul_i32 s23, s6, s16
	global_load_lds_dwordx4 v8, s[30:31]
	s_add_i32 m0, s8, 0x16000
	v_writelane_b32 v252, s37, 3
	s_mul_hi_i32 s9, s6, s16
	s_add_u32 s36, s24, s23
	v_mov_b32_e32 v143, v9
	s_addc_u32 s37, s25, s9
	s_add_i32 s9, s8, 0x2000
	v_mul_lo_u32 v19, s41, v2
	v_lshl_add_u64 v[4:5], s[30:31], 0, v[8:9]
	v_lshl_add_u64 v[6:7], s[30:31], 0, v[142:143]
	global_load_lds_dwordx4 v142, s[30:31]
	s_mov_b32 m0, s8
	s_add_u32 s30, s36, s68
	v_add_lshl_u32 v140, v19, v0, 1
	global_load_lds_dwordx4 v138, s[36:37]
	s_mov_b32 m0, s9
	s_addc_u32 s31, s37, 0
	s_add_i32 s54, s8, 0x4000
	global_load_lds_dwordx4 v140, s[36:37]
	s_mov_b32 m0, s54
	s_add_i32 s55, s8, 0x6000
	global_load_lds_dwordx4 v138, s[30:31]
	s_mov_b32 m0, s55
	v_mov_b32_e32 v139, v9
	global_load_lds_dwordx4 v140, s[30:31]
	v_mov_b32_e32 v141, v9
	v_lshl_add_u64 v[0:1], s[4:5], 0, v[8:9]
	v_lshl_add_u64 v[2:3], s[4:5], 0, v[142:143]
	v_lshl_add_u64 v[10:11], s[36:37], 0, v[138:139]
	v_lshl_add_u64 v[12:13], s[36:37], 0, v[140:141]
	s_ashr_i32 s39, s38, 31
	s_lshl_b64 s[38:39], s[38:39], 16
	s_add_u32 s44, s10, s38
	s_addc_u32 s45, s11, s39
	s_add_i32 m0, s8, 0x18000
	v_lshl_add_u64 v[0:1], v[0:1], 0, s[94:95]
	global_load_lds_dwordx4 v[0:1], off
	v_lshl_add_u64 v[0:1], v[2:3], 0, s[94:95]
	s_add_i32 m0, s8, 0x1a000
	s_add_i32 s57, s8, 0x8000
	global_load_lds_dwordx4 v[0:1], off
	v_lshl_add_u64 v[0:1], v[10:11], 0, s[94:95]
	s_mov_b32 m0, s57
	s_add_i32 s58, s8, 0xa000
	global_load_lds_dwordx4 v[0:1], off
	v_lshl_add_u64 v[0:1], v[12:13], 0, s[94:95]
	s_mov_b32 m0, s58
	v_bfe_u32 v20, v170, 4, 2
	global_load_lds_dwordx4 v[0:1], off
	s_add_i32 m0, s8, 0x1c000
	v_lshl_add_u64 v[0:1], v[4:5], 0, s[94:95]
	global_load_lds_dwordx4 v[0:1], off
	v_lshl_add_u64 v[0:1], v[6:7], 0, s[94:95]
	s_add_i32 m0, s8, 0x1e000
	v_and_b32_e32 v21, 15, v170
	global_load_lds_dwordx4 v[0:1], off
	s_cmp_eq_u32 s42, 1
	s_cselect_b64 s[30:31], -1, 0
	s_cmp_lg_u32 s42, 1
	s_cbranch_scc1 .LBB0_812
	s_barrier
.LBB0_812:
	s_waitcnt vmcnt(8)
	s_barrier
	v_lshlrev_b32_e32 v22, 4, v20
	v_lshl_or_b32 v171, s42, 6, v21
	v_lshl_or_b32 v21, v21, 6, v22
	v_lshlrev_b32_e32 v22, 2, v170
	s_lshl_b32 s38, s42, 13
	v_and_b32_e32 v22, 32, v22
	v_bitop3_b32 v23, v21, s38, v22 bitop3:0xde
	s_lshl_b32 s38, s43, 5
	v_add_u32_e32 v0, v19, v17
	s_lshr_b32 s56, s41, 6
	s_and_b32 s41, s38, 0x60
	v_add_lshl_u32 v0, v0, v18, 1
	v_mov_b32_e32 v1, v9
	s_lshl_b32 s38, s41, 7
	s_waitcnt vmcnt(6)
	s_add_i32 s59, s56, -2
	v_lshl_add_u64 v[144:145], s[68:69], 0, v[0:1]
	v_add_u32_e32 v0, v16, v14
	s_cmpk_lt_u32 s40, 0x100
	v_add_lshl_u32 v0, v0, v15, 1
	s_mov_b32 s23, s22
	s_mov_b32 s34, s22
	s_mov_b32 s35, s22
	v_bitop3_b32 v172, s38, v21, v22 bitop3:0xf6
	s_cselect_b64 s[46:47], -1, 0
	s_mov_b32 s60, 0
	v_cmp_eq_u32_e64 s[38:39], 0, v20
	s_ashr_i32 s61, s89, 31
	s_ashr_i32 s62, s90, 31
	v_lshl_or_b32 v173, v20, 3, s41
	v_lshl_add_u64 v[146:147], s[68:69], 0, v[0:1]
	v_add_u32_e32 v174, 0, v23
	s_barrier
	s_branch .LBB0_815

.LBB0_933:
	s_andn2_b64 vcc, exec, s[36:37]
	s_cbranch_vccnz .LBB0_950
	s_cmpk_gt_i32 s90, 0x57f
	v_readfirstlane_b32 s17, v170
	s_cbranch_scc1 .LBB0_950
	v_lshlrev_b32_e32 v0, 4, v170
	s_waitcnt lgkmcnt(0)
	v_add_u32_e32 v1, 0x2000, v0
	v_ashrrev_i32_e32 v2, 31, v1
	v_lshrrev_b32_e32 v2, 22, v2
	v_add_u32_e32 v2, v1, v2
	v_ashrrev_i32_e32 v8, 10, v2
	v_mul_i32_i24_e32 v2, 0x400, v8
	v_sub_u32_e32 v1, v1, v2
	v_lshrrev_b32_e32 v2, 4, v1
	v_bitop3_b32 v1, v2, v1, 32 bitop3:0x6c
	v_ashrrev_i32_e32 v2, 31, v1
	v_lshrrev_b32_e32 v2, 26, v2
	v_add_u32_e32 v2, v1, v2
	v_lshlrev_b32_e32 v3, 3, v8
	v_readlane_b32 s2, v254, 53
	v_readlane_b32 s4, v254, 61
	v_ashrrev_i32_e32 v10, 6, v2
	v_and_b32_e32 v3, -16, v3
	s_add_u32 s6, s4, s2
	v_readlane_b32 s2, v254, 52
	v_readlane_b32 s4, v254, 62
	v_add_u32_e32 v3, v10, v3
	s_addc_u32 s7, s4, s2
	v_and_b32_e32 v4, 3, v10
	s_mov_b32 s2, 0xfffe0
	v_lshrrev_b32_e32 v5, 2, v3
	v_lshlrev_b32_e32 v6, 1, v3
	v_and_b32_e32 v2, 0xc0, v2
	v_and_or_b32 v4, v3, s2, v4
	v_and_b32_e32 v5, 4, v5
	v_and_b32_e32 v6, 24, v6
	v_sub_u32_e32 v1, v1, v2
	v_or3_b32 v4, v4, v5, v6
	v_lshlrev_b32_e32 v5, 5, v8
	v_ashrrev_i16_sdwa v1, v185, sext(v1) dst_sel:DWORD dst_unused:UNUSED_PAD src0_sel:DWORD src1_sel:BYTE_0
	v_and_b32_e32 v5, 32, v5
	v_bfe_i32 v11, v1, 0, 16
	v_add_lshl_u32 v1, v5, v11, 1
	v_lshl_add_u32 v130, v4, 12, v1
	v_lshl_add_u32 v132, v3, 12, v1
	v_bfe_i32 v1, v170, 27, 1
	v_lshrrev_b32_e32 v1, 22, v1
	v_add_u32_e32 v1, v0, v1
	v_and_b32_e32 v1, 0xfffffc00, v1
	v_sub_u32_e32 v0, v0, v1
	v_lshrrev_b32_e32 v1, 4, v0
	v_ashrrev_i32_e32 v2, 31, v170
	v_bitop3_b32 v0, v1, v0, 32 bitop3:0x6c
	v_lshrrev_b32_e32 v2, 26, v2
	v_ashrrev_i32_e32 v1, 31, v0
	v_add_u32_e32 v2, v170, v2
	s_ashr_i32 s9, s90, 31
	v_lshrrev_b32_e32 v1, 26, v1
	v_ashrrev_i32_e32 v13, 6, v2
	s_lshr_b32 s4, s9, 29
	v_add_u32_e32 v1, v0, v1
	v_lshlrev_b32_e32 v2, 3, v13
	s_add_i32 s4, s90, s4
	s_ashr_i32 s16, s17, 6
	v_ashrrev_i32_e32 v12, 6, v1
	v_and_b32_e32 v2, -16, v2
	s_ashr_i32 s5, s4, 3
	s_and_b32 s4, s4, -8
	s_ashr_i32 s23, s17, 8
	s_lshl_b32 s8, s16, 10
	v_add_u32_e32 v2, v12, v2
	v_and_b32_e32 v3, 3, v12
	s_sub_i32 s4, s90, s4
	v_and_or_b32 v3, v2, s2, v3
	s_cmp_lt_i32 s4, 0
	s_movk_i32 s2, 0xb1
	s_cselect_b32 s18, s2, 0xb0
	s_mul_i32 s4, s4, s18
	s_add_i32 s4, s4, s5
	s_mul_hi_i32 s5, s4, 0x2e8ba2e9
	s_lshr_b32 s18, s5, 31
	s_ashr_i32 s5, s5, 6
	s_add_i32 s5, s5, s18
	s_lshl_b32 s18, s5, 3
	s_mulk_i32 s5, 0x160
	s_sub_i32 s4, s4, s5
	s_bfe_u32 s5, s4, 0x3001c
	s_add_i32 s5, s4, s5
	s_sext_i32_i16 s19, s5
	s_and_b32 s5, s5, 0xfff8
	s_sub_i32 s4, s4, s5
	s_sext_i32_i16 s4, s4
	v_lshrrev_b32_e32 v4, 2, v2
	v_lshlrev_b32_e32 v5, 1, v2
	v_and_b32_e32 v1, 0xc0, v1
	s_lshr_b32 s22, s19, 3
	s_add_i32 s34, s18, s4
	v_and_b32_e32 v4, 4, v4
	v_and_b32_e32 v5, 24, v5
	v_sub_u32_e32 v0, v0, v1
	s_ashr_i32 s35, s34, 31
	s_bfe_i64 s[4:5], s[22:23], 0x100000
	v_or3_b32 v3, v3, v4, v5
	v_lshlrev_b32_e32 v4, 5, v13
	v_ashrrev_i16_sdwa v0, v185, sext(v0) dst_sel:DWORD dst_unused:UNUSED_PAD src0_sel:DWORD src1_sel:BYTE_0
	s_lshl_b64 s[18:19], s[34:35], 20
	s_lshl_b64 s[4:5], s[4:5], 20
	v_and_b32_e32 v4, 32, v4
	v_bfe_i32 v14, v0, 0, 16
	s_add_u32 s4, s6, s4
	v_add_lshl_u32 v0, v4, v14, 1
	s_addc_u32 s5, s7, s5
	s_add_i32 s35, s8, 0
	v_lshl_add_u32 v134, v3, 12, v0
	s_add_i32 m0, s35, 0x10000
	v_lshl_add_u32 v136, v2, 12, v0
	global_load_lds_dwordx4 v134, s[4:5]
	s_add_i32 m0, s35, 0x12000
	s_add_u32 s20, s4, 0x80000
	global_load_lds_dwordx4 v130, s[4:5]
	s_addc_u32 s21, s5, 0
	s_add_i32 m0, s35, 0x14000
	v_mov_b32_e32 v135, v9
	global_load_lds_dwordx4 v134, s[20:21]
	s_add_i32 m0, s35, 0x16000
	s_add_u32 s36, s14, s18
	s_addc_u32 s37, s15, s19
	s_add_i32 s42, s35, 0x2000
	global_load_lds_dwordx4 v130, s[20:21]
	s_mov_b32 m0, s35
	s_add_u32 s18, s36, 0x80000
	global_load_lds_dwordx4 v136, s[36:37]
	s_mov_b32 m0, s42
	s_addc_u32 s19, s37, 0
	s_add_i32 s43, s35, 0x4000
	global_load_lds_dwordx4 v132, s[36:37]
	s_mov_b32 m0, s43
	s_add_i32 s44, s35, 0x6000
	global_load_lds_dwordx4 v136, s[18:19]
	s_mov_b32 m0, s44
	v_mov_b32_e32 v131, v9
	global_load_lds_dwordx4 v132, s[18:19]
	v_mov_b32_e32 v137, v9
	v_mov_b32_e32 v133, v9
	v_lshl_add_u64 v[6:7], s[4:5], 0, v[134:135]
	v_lshl_add_u64 v[4:5], s[4:5], 0, v[130:131]
	v_lshl_add_u64 v[0:1], s[36:37], 0, v[136:137]
	v_lshl_add_u64 v[2:3], s[36:37], 0, v[132:133]
	s_add_i32 m0, s35, 0x18000
	v_lshl_add_u64 v[6:7], v[6:7], 0, s[94:95]
	global_load_lds_dwordx4 v[6:7], off
	v_lshl_add_u64 v[4:5], v[4:5], 0, s[94:95]
	s_add_i32 m0, s35, 0x1a000
	s_add_i32 s45, s35, 0x8000
	s_add_i32 s46, s35, 0xa000
	global_load_lds_dwordx4 v[4:5], off
	v_lshl_add_u64 v[0:1], v[0:1], 0, s[94:95]
	s_mov_b32 m0, s45
	s_add_u32 s24, s4, 0x80080
	global_load_lds_dwordx4 v[0:1], off
	v_lshl_add_u64 v[0:1], v[2:3], 0, s[94:95]
	s_mov_b32 m0, s46
	s_addc_u32 s25, s5, 0
	global_load_lds_dwordx4 v[0:1], off
	s_add_i32 m0, s35, 0x1c000
	v_lshl_add_u64 v[0:1], s[24:25], 0, v[134:135]
	global_load_lds_dwordx4 v[0:1], off
	v_lshl_add_u64 v[0:1], s[24:25], 0, v[130:131]
	s_add_i32 m0, s35, 0x1e000
	s_nop 0
	global_load_lds_dwordx4 v[0:1], off
	s_cmp_eq_u32 s23, 1
	s_cselect_b64 s[18:19], -1, 0
	s_cmp_lg_u32 s23, 1
	s_cbranch_scc1 .LBB0_937
	s_barrier
.LBB0_937:
	v_readlane_b32 s20, v254, 54
	v_readlane_b32 s21, v254, 55
	s_add_u32 s20, s10, s20
	s_addc_u32 s21, s11, s21
	s_lshl_b32 s16, s16, 5
	s_and_b32 s27, s16, 0x60
	s_lshl_b32 s26, s23, 13
	s_lshl_b32 s28, s27, 7
	s_waitcnt vmcnt(8)
	s_barrier
	s_cmpk_lt_u32 s17, 0x100
	v_lshrrev_b32_e32 v1, 1, v170
	v_and_b32_e32 v1, 24, v1
	v_and_b32_e32 v0, 15, v170
	v_lshlrev_b32_e32 v2, 1, v1
	v_lshl_or_b32 v171, s23, 6, v0
	v_lshl_or_b32 v0, v0, 6, v2
	v_lshlrev_b32_e32 v2, 2, v170
	v_and_b32_e32 v2, 32, v2
	v_bitop3_b32 v3, v0, s26, v2 bitop3:0xde
	v_bitop3_b32 v178, s28, v0, v2 bitop3:0xf6
	v_lshlrev_b32_e32 v0, 15, v8
	v_and_b32_e32 v0, 0xffff0000, v0
	v_or_b32_e32 v179, s27, v1
	v_lshl_add_u32 v0, v10, 12, v0
	v_and_b32_e32 v1, 1, v8
	v_lshl_or_b32 v0, v1, 6, v0
	v_lshl_add_u32 v138, v11, 1, v0
	v_lshlrev_b32_e32 v0, 15, v13
	v_and_b32_e32 v0, 0xffff0000, v0
	s_waitcnt vmcnt(6)
	v_lshl_add_u32 v0, v12, 12, v0
	v_and_b32_e32 v1, 1, v13
	v_lshl_or_b32 v0, v1, 6, v0
	s_sext_i32_i16 s16, s22
	s_cselect_b64 s[22:23], -1, 0
	s_ashr_i32 s47, s89, 31
	v_mov_b32_e32 v139, v9
	v_lshl_add_u32 v140, v14, 1, v0
	v_mov_b32_e32 v141, v9
	s_mov_b32 s48, 0
	v_add_u32_e32 v180, 0, v3
	s_barrier
	s_branch .LBB0_940
